# v6 + LRU gate loop xcf reads issued together, LRU cross-segment scan with two LDS read groups in flight, attention context K/V staging loads issued together before the barrier; pad keeps later code ad
# speedup vs baseline: 1.0089x; 1.0019x over previous
; #define LAS __attribute__((address_space(3)))
; __device__ __forceinline__ float fast_sigmoid(float x) { return __builtin_amdgcn_rcpf(1.0f + __builtin_amdgcn_exp2f(-1.44269504089f * x)); }
; __device__ __forceinline__ void lds_barrier() { asm volatile("s_waitcnt lgkmcnt(0)" ::: "memory"); __builtin_amdgcn_s_barrier(); asm volatile("" ::: "memory"); }
; __device__ __forceinline__ void lru_item(const Params& p, LAS unsigned char* lds, int item, int tid, int lane, int wave) {
;     ...
;             for (int q = 0; q < 4; ++q) {
;                 const int tb = tb0 + q;
;                 const bf16x8 a0 = *(const LAS bf16x8*)(xcb + (16 * tb + l15) * 72 + 8 * g), a1 = *(const LAS bf16x8*)(xcb + (16 * tb + l15) * 72 + 8 * g + 32);
;                 f32x4 gr_ = (f32x4){0.f, 0.f, 0.f, 0.f}, gi_ = (f32x4){0.f, 0.f, 0.f, 0.f};
;                 gr_ = __builtin_amdgcn_mfma_f32_16x16x32_bf16(a0, Bg[0][0], gr_, 0, 0, 0); gr_ = __builtin_amdgcn_mfma_f32_16x16x32_bf16(a1, Bg[0][1], gr_, 0, 0, 0);
;                 gi_ = __builtin_amdgcn_mfma_f32_16x16x32_bf16(a0, Bg[1][0], gi_, 0, 0, 0); gi_ = __builtin_amdgcn_mfma_f32_16x16x32_bf16(a1, Bg[1][1], gi_, 0, 0, 0);
; #pragma unroll
;                 for (int e = 0; e < 4; ++e) {
;                     const int tl = 16 * tb + 4 * g + e;
;                     const float rg = fast_sigmoid(gr_[e] + br), ig = fast_sigmoid(gi_[e] + bi);
;                     const float la2 = sp8 * rg, a = __builtin_amdgcn_exp2f(la2);
;                     const float em = __builtin_fmaf(-a, a, 1.0f);
;                     As[tl * 33 + jl] = a; Us[tl * 33 + jl] = __builtin_amdgcn_sqrtf(em) * ig * xcf[tl * 33 + jl];
;                 }
;             }
;             lds_barrier();
;             float av[16], uv[16];
;             {
;                 float A = 1.f, H = 0.f;
;                 const LAS float* ap_ = As + (dir ? (LCH - 1 - 16 * sg) : 16 * sg) * 33 + sc; const LAS float* up_ = Us + (dir ? (LCH - 1 - 16 * sg) : 16 * sg) * 33 + sc;
; #pragma unroll
;                 for (int e = 0; e < 16; ++e) { av[e] = dir ? ap_[-e * 33] : ap_[e * 33]; uv[e] = dir ? up_[-e * 33] : up_[e * 33]; H = av[e] * H + uv[e]; A *= av[e]; }
;                 segA[sg * 32 + sc] = A; segH[sg * 32 + sc] = H;
.LBB0_2180:
	ds_read_b128 v[86:89], v53
	ds_read_b128 v[90:93], v53 offset:64
	v_add_u32_e32 v224, s54, v167
	ds_read_b32 v98, v224
	ds_read_b32 v99, v224 offset:132
	ds_read_b32 v100, v224 offset:264
	ds_read_b32 v101, v224 offset:396
	v_add_u32_e32 v53, 0x900, v53
	s_waitcnt lgkmcnt(5)
	v_mfma_f32_16x16x32_bf16 v[94:97], v[86:89], v[2:5], 0
	s_waitcnt lgkmcnt(4)
	v_mfma_f32_16x16x32_bf16 v[94:97], v[90:93], v[6:9], v[94:97]
	v_mfma_f32_16x16x32_bf16 v[86:89], v[86:89], v[10:13], 0
	v_mfma_f32_16x16x32_bf16 v[86:89], v[90:93], v[14:17], v[86:89]
	s_nop 5
	v_add_f32_e32 v90, v55, v94
	v_mul_f32_e32 v90, 0xbfb8aa3b, v90
	v_exp_f32_e32 v90, v90
	v_add_u32_e32 v92, s54, v167
	v_add_u32_e32 v93, 0x11400, v92
	v_add_f32_e32 v86, v57, v86
	v_add_f32_e32 v90, 1.0, v90
	v_rcp_f32_e32 v90, v90
	v_mul_f32_e32 v86, 0xbfb8aa3b, v86
	v_exp_f32_e32 v86, v86
	v_add_f32_e32 v87, v57, v87
	v_mul_f32_e32 v90, v215, v90
	v_exp_f32_e32 v90, v90
	v_add_f32_e32 v86, 1.0, v86
	v_rcp_f32_e32 v86, v86
	v_mul_f32_e32 v87, 0xbfb8aa3b, v87
	v_fma_f32 v91, -v90, v90, 1.0
	ds_write_b32 v93, v90
	v_sqrt_f32_e32 v90, v91
	v_exp_f32_e32 v87, v87
	v_mul_f32_e32 v86, v86, v90
	v_add_f32_e32 v87, 1.0, v87
	v_rcp_f32_e32 v87, v87
	s_waitcnt lgkmcnt(1)
	v_mul_f32_e32 v86, v98, v86
	v_add_u32_e32 v90, s54, v168
	v_add_u32_e32 v91, 0x19800, v90
	ds_write_b32 v91, v86
	v_add_f32_e32 v86, v55, v95
	v_mul_f32_e32 v86, 0xbfb8aa3b, v86
	v_exp_f32_e32 v86, v86
	v_add_u32_e32 v93, 0x11484, v90
	s_addk_i32 s54, 0x840
	s_cmpk_eq_i32 s54, 0x2100
	v_add_f32_e32 v86, 1.0, v86
	v_rcp_f32_e32 v86, v86
	s_nop 0
	v_mul_f32_e32 v86, v215, v86
	v_exp_f32_e32 v86, v86
	ds_write_b32 v93, v86
	v_fma_f32 v91, -v86, v86, 1.0
	v_sqrt_f32_e32 v86, v91
	v_add_u32_e32 v91, 0x11508, v90
	v_mul_f32_e32 v86, v87, v86
	v_mul_f32_e32 v86, v99, v86
	v_add_u32_e32 v87, 0x19884, v90
	ds_write_b32 v87, v86
	v_add_f32_e32 v86, v55, v96
	v_mul_f32_e32 v86, 0xbfb8aa3b, v86
	v_exp_f32_e32 v86, v86
	v_add_f32_e32 v87, v57, v88
	v_mul_f32_e32 v87, 0xbfb8aa3b, v87
	v_exp_f32_e32 v87, v87
	v_add_f32_e32 v86, 1.0, v86
	v_rcp_f32_e32 v86, v86
	v_add_f32_e32 v87, 1.0, v87
	v_rcp_f32_e32 v87, v87
	v_mul_f32_e32 v86, v215, v86
	v_exp_f32_e32 v86, v86
	ds_write_b32 v91, v86
	v_fma_f32 v88, -v86, v86, 1.0
	v_sqrt_f32_e32 v86, v88
	s_nop 0
	v_mul_f32_e32 v86, v87, v86
	v_mul_f32_e32 v86, v100, v86
	v_add_u32_e32 v87, 0x19908, v90
	ds_write_b32 v87, v86
	v_add_f32_e32 v86, v55, v97
	v_mul_f32_e32 v86, 0xbfb8aa3b, v86
	v_exp_f32_e32 v86, v86
	v_add_f32_e32 v87, v57, v89
	v_mul_f32_e32 v87, 0xbfb8aa3b, v87
	v_exp_f32_e32 v87, v87
	v_add_f32_e32 v86, 1.0, v86
	v_rcp_f32_e32 v86, v86
	v_add_u32_e32 v89, 0x1158c, v90
	v_add_f32_e32 v87, 1.0, v87
	v_rcp_f32_e32 v87, v87
	v_mul_f32_e32 v86, v215, v86
	v_exp_f32_e32 v86, v86
	ds_write_b32 v89, v86
	v_fma_f32 v88, -v86, v86, 1.0
	v_sqrt_f32_e32 v86, v88
	s_nop 0
	v_mul_f32_e32 v86, v87, v86
	v_mul_f32_e32 v86, v86, v101
	v_add_u32_e32 v87, 0x1998c, v92
	ds_write_b32 v87, v86
	s_cbranch_scc0 .LBB0_2180
	v_sub_u32_e64 v53, s69, 1 clamp
	s_waitcnt lgkmcnt(0)
	s_barrier
	v_readfirstlane_b32 s92, v53
	v_add_u32_e32 v53, s70, v216
	v_add_u32_e32 v86, s70, v217
	v_add_u32_e32 v87, s71, v216
	v_add_u32_e32 v88, s71, v217
	v_add_u32_e32 v89, s72, v216
	v_add_u32_e32 v90, s72, v217
	ds_read_b32 v238, v216
	ds_read_b32 v224, v217
	ds_read_b32 v236, v53
	ds_read_b32 v106, v86
	ds_read_b32 v237, v87
	ds_read_b32 v98, v88
	ds_read_b32 v99, v89
	ds_read_b32 v91, v90
	s_waitcnt lgkmcnt(6)
	v_fma_f32 v53, 0, v238, v224
	s_waitcnt lgkmcnt(4)
	v_fma_f32 v53, v53, v236, v106
	v_mul_f32_e32 v86, v238, v236
	s_waitcnt lgkmcnt(2)
	v_fma_f32 v53, v53, v237, v98
	v_mul_f32_e32 v86, v86, v237
	s_waitcnt lgkmcnt(0)
	v_fma_f32 v87, v53, v99, v91
	v_add_u32_e32 v53, s73, v216
	v_add_u32_e32 v93, s75, v217
	v_mul_f32_e32 v86, v86, v99
	v_add_u32_e32 v88, s73, v217
	v_add_u32_e32 v89, s74, v216
	v_add_u32_e32 v90, s74, v217
	v_add_u32_e32 v92, s75, v216
	v_add_u32_e32 v94, s78, v216
	v_add_u32_e32 v96, s78, v217
	ds_read_b32 v232, v53
	ds_read_b32 v225, v88
	ds_read_b32 v227, v89
	ds_read_b32 v101, v90
	ds_read_b32 v103, v92
	ds_read_b32 v93, v93
	ds_read_b32 v95, v94
	ds_read_b32 v53, v96
	s_waitcnt lgkmcnt(7)
	v_mul_f32_e32 v86, v86, v232
	s_waitcnt lgkmcnt(6)
	v_fma_f32 v87, v87, v232, v225
	s_waitcnt lgkmcnt(5)
	v_mul_f32_e32 v86, v86, v227
	s_cmp_lg_u32 s69, 0
	s_waitcnt lgkmcnt(4)
	v_fma_f32 v87, v87, v227, v101
	s_waitcnt lgkmcnt(3)
	v_mul_f32_e32 v86, v86, v103
	v_add_u32_e32 v88, s79, v216
	v_add_u32_e32 v90, s80, v216
	v_add_u32_e32 v94, s81, v216
	v_add_u32_e32 v96, s81, v217
	s_cselect_b64 s[54:55], -1, 0
	s_waitcnt lgkmcnt(2)
	v_fma_f32 v87, v87, v103, v93
	s_waitcnt lgkmcnt(1)
	v_mul_f32_e32 v86, v86, v95
	v_add_u32_e32 v89, s79, v217
	v_add_u32_e32 v92, s80, v217
	v_add_u32_e32 v97, s82, v216
	v_add_u32_e32 v100, s82, v217
	ds_read_b32 v233, v88
	ds_read_b32 v226, v89
	ds_read_b32 v229, v90
	ds_read_b32 v102, v92
	ds_read_b32 v104, v94
	ds_read_b32 v94, v96
	ds_read_b32 v96, v97
	ds_read_b32 v90, v100
	s_and_b64 s[56:57], s[54:55], exec
	s_waitcnt lgkmcnt(8)
	v_fma_f32 v87, v87, v95, v53
	s_waitcnt lgkmcnt(7)
	v_mul_f32_e32 v86, v86, v233
	s_cselect_b32 s56, 7, 0
	s_waitcnt lgkmcnt(6)
	v_fma_f32 v87, v87, v233, v226
	s_waitcnt lgkmcnt(5)
	v_mul_f32_e32 v86, v86, v229
	s_cselect_b32 s91, s68, s67
	s_sub_i32 s93, s56, s92
	s_waitcnt lgkmcnt(4)
	v_fma_f32 v87, v87, v229, v102
	s_waitcnt lgkmcnt(3)
	v_mul_f32_e32 v86, v86, v104
	v_add_u32_e32 v88, s83, v216
	v_add_u32_e32 v92, s88, v216
	v_add_u32_e32 v97, s88, v217
	v_add_u32_e32 v100, s89, v216
	s_and_b64 s[56:57], s[48:49], exec
	s_waitcnt lgkmcnt(2)
	v_fma_f32 v87, v87, v104, v94
	s_waitcnt lgkmcnt(1)
	v_mul_f32_e32 v86, v86, v96
	v_add_u32_e32 v89, s83, v217
	v_add_u32_e32 v235, s89, v217
	v_add_u32_e32 v239, s90, v216
	v_add_u32_e32 v240, s90, v217
	ds_read_b32 v234, v88
	ds_read_b32 v230, v89
	ds_read_b32 v231, v92
	ds_read_b32 v105, v97
	ds_read_b32 v107, v100
	ds_read_b32 v97, v235
	ds_read_b32 v100, v239
	ds_read_b32 v92, v240
	s_cselect_b32 s56, s92, s93
	s_waitcnt lgkmcnt(8)
	v_fma_f32 v87, v87, v96, v90
	s_waitcnt lgkmcnt(7)
	v_mul_f32_e32 v86, v86, v234
	s_lshl_b32 s92, s56, 8
	s_waitcnt lgkmcnt(6)
	v_fma_f32 v87, v87, v234, v230
	s_waitcnt lgkmcnt(5)
	v_mul_f32_e32 v86, v86, v231
	s_sub_i32 s56, s91, s58
	s_waitcnt lgkmcnt(4)
	v_fma_f32 v87, v87, v231, v105
	s_waitcnt lgkmcnt(3)
	v_mul_f32_e32 v86, v86, v107
	s_add_i32 s56, s56, s92
	s_and_b64 s[94:95], s[46:47], s[54:55]
	s_waitcnt lgkmcnt(2)
	v_fma_f32 v87, v87, v107, v97
	s_waitcnt lgkmcnt(1)
	v_mul_f32_e32 v86, v86, v100
	s_addk_i32 s56, 0xef
	s_and_b64 vcc, exec, s[94:95]
	s_waitcnt lgkmcnt(0)
	v_fma_f32 v87, v87, v100, v92
	ds_write_b32 v122, v86
	ds_write_b32 v123, v87
	s_cbranch_vccz .LBB0_2183
; __device__ __forceinline__ void lru_item(const Params& p, LAS unsigned char* lds, int item, int tid, int lane, int wave) {
;     ...
;             const int rbase = dir == 0 ? base + t0 + 32 * wave : base + t0 + LCH - 1 - 32 * wave - 16;
;             float hfv[16]; unsigned grv[16];
;             if (!isctx && dir == 1) {
;                 const float* hp_ = HF + (size_t)rbase * 1024; const bf16* gp_ = ZO + (size_t)rbase * ZO_LD;
; #pragma unroll
;                 for (int e = 0; e < 16; ++e) { hfv[e] = (hp_ - (size_t)e * 1024)[hoff]; grv[e] = (unsigned)(gp_ - (size_t)e * ZO_LD)[goff]; }
;             }
	s_ashr_i32 s57, s56, 31
	s_lshl_b64 s[94:95], s[56:57], 12
	v_lshl_add_u64 v[88:89], v[80:81], 0, s[94:95]
	v_mad_i64_i32 v[86:87], s[94:95], s56, v180, v[82:83]
	v_add_co_u32_e32 v184, vcc, 0x2000, v86
	global_load_dword v183, v[88:89], off
	s_nop 0
	v_addc_co_u32_e32 v185, vcc, 0, v87, vcc
	v_add_co_u32_e32 v188, vcc, 0xffffe000, v88
	global_load_ushort v186, v[184:185], off
	s_nop 0
	global_load_dword v184, v[88:89], off offset:-4096
	global_load_ushort v187, v[86:87], off offset:-2048
	v_addc_co_u32_e32 v189, vcc, -1, v89, vcc
	global_load_dword v185, v[188:189], off
	v_add_co_u32_e32 v188, vcc, 0xffffd000, v86
	s_movk_i32 s57, 0x8000
	s_nop 0
	v_addc_co_u32_e32 v189, vcc, -1, v87, vcc
	v_add_co_u32_e32 v190, vcc, 0xffffd000, v88
	global_load_ushort v189, v[188:189], off
	s_nop 0
	v_addc_co_u32_e32 v191, vcc, -1, v89, vcc
	global_load_dword v188, v[190:191], off
	v_add_co_u32_e32 v190, vcc, 0xffffb000, v86
	s_nop 1
	v_addc_co_u32_e32 v191, vcc, -1, v87, vcc
	v_add_co_u32_e32 v192, vcc, 0xffffc000, v88
	global_load_ushort v191, v[190:191], off offset:-2048
	s_nop 0
	v_addc_co_u32_e32 v193, vcc, -1, v89, vcc
	global_load_dword v190, v[192:193], off
	v_add_co_u32_e32 v192, vcc, 0xffff8000, v86
	s_nop 1
	v_addc_co_u32_e32 v193, vcc, -1, v87, vcc
	v_add_co_u32_e32 v194, vcc, 0xffffb000, v88
	global_load_ushort v193, v[192:193], off
	s_nop 0
	v_addc_co_u32_e32 v195, vcc, -1, v89, vcc
	global_load_dword v192, v[194:195], off
	v_add_co_u32_e32 v194, vcc, 0xffff6000, v86
	s_nop 1
	v_addc_co_u32_e32 v195, vcc, -1, v87, vcc
	v_add_co_u32_e32 v196, vcc, 0xffffa000, v88
	global_load_ushort v195, v[194:195], off offset:-2048
	s_nop 0
	v_addc_co_u32_e32 v197, vcc, -1, v89, vcc
	global_load_dword v194, v[196:197], off
	v_add_co_u32_e32 v196, vcc, 0xffff3000, v86
	s_nop 1
	v_addc_co_u32_e32 v197, vcc, -1, v87, vcc
	v_add_co_u32_e32 v198, vcc, 0xffff9000, v88
	global_load_ushort v197, v[196:197], off
	s_nop 0
	v_addc_co_u32_e32 v199, vcc, -1, v89, vcc
	global_load_dword v196, v[198:199], off
	v_add_co_u32_e32 v198, vcc, 0xffff1000, v86
	s_nop 1
	v_addc_co_u32_e32 v199, vcc, -1, v87, vcc
	v_add_co_u32_e32 v200, vcc, s57, v88
	global_load_ushort v199, v[198:199], off offset:-2048
	s_nop 0
	v_addc_co_u32_e32 v201, vcc, -1, v89, vcc
	global_load_dword v198, v[200:201], off
	v_add_co_u32_e32 v200, vcc, 0xfffee000, v86
	s_mov_b32 s57, 0xffff6000
	s_nop 0
	v_addc_co_u32_e32 v201, vcc, -1, v87, vcc
	v_add_co_u32_e32 v202, vcc, 0xffff7000, v88
	global_load_ushort v201, v[200:201], off
	s_nop 0
	v_addc_co_u32_e32 v203, vcc, -1, v89, vcc
	global_load_dword v200, v[202:203], off
	v_add_co_u32_e32 v202, vcc, 0xfffec000, v86
	s_nop 1
	v_addc_co_u32_e32 v203, vcc, -1, v87, vcc
	v_add_co_u32_e32 v204, vcc, s57, v88
	global_load_ushort v203, v[202:203], off offset:-2048
	s_nop 0
	v_addc_co_u32_e32 v205, vcc, -1, v89, vcc
	global_load_dword v202, v[204:205], off
	v_add_co_u32_e32 v204, vcc, 0xfffe9000, v86
	s_mov_b32 s57, 0xffff3000
	s_nop 0
	v_addc_co_u32_e32 v205, vcc, -1, v87, vcc
	v_add_co_u32_e32 v206, vcc, 0xffff5000, v88
	global_load_ushort v205, v[204:205], off
	s_nop 0
	v_addc_co_u32_e32 v207, vcc, -1, v89, vcc
	global_load_dword v204, v[206:207], off
	v_add_co_u32_e32 v206, vcc, 0xfffe7000, v86
	s_nop 1
	v_addc_co_u32_e32 v207, vcc, -1, v87, vcc
	v_add_co_u32_e32 v208, vcc, 0xffff4000, v88
	global_load_ushort v207, v[206:207], off offset:-2048
	s_nop 0
	v_addc_co_u32_e32 v209, vcc, -1, v89, vcc
	global_load_dword v206, v[208:209], off
	v_add_co_u32_e32 v208, vcc, 0xfffe4000, v86
	s_nop 1
	v_addc_co_u32_e32 v209, vcc, -1, v87, vcc
	v_add_co_u32_e32 v210, vcc, s57, v88
	global_load_ushort v209, v[208:209], off
	s_nop 0
	v_addc_co_u32_e32 v211, vcc, -1, v89, vcc
	global_load_dword v208, v[210:211], off
	v_add_co_u32_e32 v210, vcc, 0xfffe2000, v86
	s_nop 1
	v_addc_co_u32_e32 v211, vcc, -1, v87, vcc
	s_waitcnt vmcnt(28)
	v_add_co_u32_e32 v212, vcc, 0xffff2000, v88
	global_load_ushort v211, v[210:211], off offset:-2048
	s_nop 0
	v_addc_co_u32_e32 v213, vcc, -1, v89, vcc
	global_load_dword v210, v[212:213], off
	v_add_co_u32_e32 v212, vcc, 0xfffdf000, v86
	s_nop 1
	v_addc_co_u32_e32 v213, vcc, -1, v87, vcc
	v_add_co_u32_e32 v88, vcc, 0xffff1000, v88
	global_load_ushort v213, v[212:213], off
	s_nop 0
	v_addc_co_u32_e32 v89, vcc, -1, v89, vcc
	v_add_co_u32_e32 v86, vcc, 0xfffdd000, v86
	global_load_dword v212, v[88:89], off
	s_nop 0
	v_addc_co_u32_e32 v87, vcc, -1, v87, vcc
	global_load_ushort v214, v[86:87], off offset:-2048
; __device__ __forceinline__ unsigned cvt_pk_bf16(float lo, float hi) { unsigned r; asm volatile("v_cvt_pk_bf16_f32 %0, %1, %2" : "=v"(r) : "v"(lo), "v"(hi)); return r; }
; __device__ __forceinline__ void lds_barrier() { asm volatile("s_waitcnt lgkmcnt(0)" ::: "memory"); __builtin_amdgcn_s_barrier(); asm volatile("" ::: "memory"); }
; __device__ __forceinline__ float gelu_tanh(float x) { const float z = 0.7978845608028654f * (x + 0.044715f * x * x * x); return x * fast_sigmoid(2.0f * z); }
; __device__ __forceinline__ void lru_item(const Params& p, LAS unsigned char* lds, int item, int tid, int lane, int wave) {
;     ...
;             lds_barrier();
;             {
;                 float hin = carry, mine = 0.f;
; #pragma unroll
;                 for (int s2 = 0; s2 < 16; ++s2) { if (s2 == sg) mine = hin; hin = segA[s2 * 32 + sc] * hin + segH[s2 * 32 + sc]; }
;                 carry = hin;
;                 if (!isctx) {
;                     float hcur = mine;
;                     if (dir == 0) {
;                         float* hp_ = HF + (size_t)rbase * 1024;
; #pragma unroll
;                         for (int e = 0; e < 16; ++e) { hcur = av[e] * hcur + uv[e]; (hp_ + (size_t)e * 1024)[hoff] = hcur; }
;                     } else {
;                         bf16* mp_ = MIX + (size_t)rbase * D;
; #pragma unroll
;                         for (int e = 0; e < 16; ++e) { hcur = av[e] * hcur + uv[e];
;                             { const float o_ = (hfv[e] + hcur) * gelu_tanh(__builtin_bit_cast(float, grv[e] << 16)); (mp_ - (size_t)e * D)[moff] = (bf16)pg8::cvt_pk_bf16(o_, o_); } }
;                     }
.LBB0_2183:
	s_waitcnt lgkmcnt(0)
	s_barrier
	ds_read_b32 v88, v135
	ds_read_b32 v86, v136
	ds_read_b32 v251, v137
	ds_read_b32 v87, v138
	ds_read_b32 v235, v139
	ds_read_b32 v239, v140
	ds_read_b32 v250, v141
	ds_read_b32 v240, v142
	s_andn2_b64 vcc, exec, s[54:55]
	s_waitcnt lgkmcnt(4)
	v_fmac_f32_e32 v86, v223, v88
	v_fmac_f32_e32 v87, v86, v251
	ds_read_b32 v88, v143
	ds_read_b32 v241, v144
	ds_read_b32 v251, v145
	ds_read_b32 v242, v146
	s_waitcnt lgkmcnt(4)
	v_fmac_f32_e32 v239, v87, v235
	v_fmac_f32_e32 v240, v239, v250
	ds_read_b32 v235, v147
	ds_read_b32 v243, v148
	ds_read_b32 v250, v149
	ds_read_b32 v244, v150
	s_waitcnt lgkmcnt(4)
	v_fmac_f32_e32 v241, v240, v88
	v_fmac_f32_e32 v242, v241, v251
	ds_read_b32 v88, v151
	ds_read_b32 v245, v152
	ds_read_b32 v251, v153
	ds_read_b32 v246, v154
	s_waitcnt lgkmcnt(4)
	v_fmac_f32_e32 v243, v242, v235
	v_fmac_f32_e32 v244, v243, v250
	ds_read_b32 v235, v155
	ds_read_b32 v247, v156
	ds_read_b32 v89, v157
	ds_read_b32 v248, v158
	s_waitcnt lgkmcnt(4)
	v_fmac_f32_e32 v245, v244, v88
	v_fmac_f32_e32 v246, v245, v251
	ds_read_b32 v88, v159
	ds_read_b32 v249, v160
	ds_read_b32 v251, v161
	ds_read_b32 v250, v162
	s_waitcnt lgkmcnt(4)
	v_fmac_f32_e32 v247, v246, v235
	v_fmac_f32_e32 v248, v247, v89
	s_waitcnt lgkmcnt(0)
	v_fmac_f32_e32 v249, v248, v88
	v_fmac_f32_e32 v250, v249, v251
	ds_read_b32 v251, v163
	ds_read_b32 v89, v164
	ds_read_b32 v235, v165
	ds_read_b32 v88, v166
	s_waitcnt lgkmcnt(2)
	v_fmac_f32_e32 v89, v250, v251
	s_cbranch_vccnz .LBB0_2188
	v_cndmask_b32_e64 v223, 0, v223, s[6:7]
	v_cndmask_b32_e64 v86, v223, v86, s[8:9]
	v_cndmask_b32_e64 v86, v86, v87, s[10:11]
	v_cndmask_b32_e64 v86, v86, v239, s[12:13]
	v_cndmask_b32_e64 v86, v86, v240, s[14:15]
	v_cndmask_b32_e64 v86, v86, v241, s[16:17]
	v_cndmask_b32_e64 v86, v86, v242, s[18:19]
	v_cndmask_b32_e64 v86, v86, v243, s[20:21]
	v_cndmask_b32_e64 v86, v86, v244, s[22:23]
	v_cndmask_b32_e64 v86, v86, v245, s[24:25]
	v_cndmask_b32_e64 v86, v86, v246, s[26:27]
	v_cndmask_b32_e64 v86, v86, v247, s[28:29]
	v_cndmask_b32_e64 v86, v86, v248, s[30:31]
	v_cndmask_b32_e64 v86, v86, v249, s[34:35]
	v_cndmask_b32_e64 v86, v86, v250, s[36:37]
	v_cndmask_b32_e64 v86, v86, v89, s[38:39]
	v_fmac_f32_e32 v224, v238, v86
	v_fmac_f32_e32 v106, v236, v224
	s_mov_b64 s[54:55], -1
	s_and_b64 vcc, exec, s[52:53]
	v_fmac_f32_e32 v98, v237, v106
	s_cbranch_vccz .LBB0_2186
	s_waitcnt vmcnt(30)
	v_lshlrev_b32_e32 v236, 16, v186
	v_mul_f32_e32 v237, 0x3d372713, v236
	v_mul_f32_e32 v237, v237, v236
	v_fma_f32 v237, v237, v236, v236
	v_mul_f32_e32 v237, 0x3f4c422a, v237
	v_add_f32_e32 v237, v237, v237
	v_mul_f32_e32 v237, 0xbfb8aa3b, v237
	v_exp_f32_e32 v237, v237
	s_ashr_i32 s57, s56, 31
	s_lshl_b64 s[54:55], s[56:57], 12
	v_lshl_add_u64 v[86:87], v[84:85], 0, s[54:55]
	v_add_f32_e32 v237, 1.0, v237
	v_rcp_f32_e32 v237, v237
	v_add_f32_e32 v223, v183, v224
	s_mov_b32 s54, 0x39600000
	v_mul_f32_e32 v236, v237, v236
	v_mul_f32_e32 v223, v236, v223
	v_add_co_u32_e32 v236, vcc, s54, v86
	v_cvt_pk_bf16_f32 v223, v223, v223
	s_mov_b32 s54, 0x395ff000
	s_nop 0
	v_addc_co_u32_e32 v237, vcc, 0, v87, vcc
	global_store_short v[236:237], v223, off offset:2048
	s_waitcnt vmcnt(29)
	v_lshlrev_b32_e32 v236, 16, v187
	v_mul_f32_e32 v237, 0x3d372713, v236
	v_mul_f32_e32 v237, v237, v236
	v_fma_f32 v237, v237, v236, v236
	v_mul_f32_e32 v237, 0x3f4c422a, v237
	v_add_f32_e32 v237, v237, v237
	v_mul_f32_e32 v237, 0xbfb8aa3b, v237
	v_exp_f32_e32 v237, v237
	v_add_f32_e32 v223, v184, v106
	v_add_f32_e32 v237, 1.0, v237
	v_rcp_f32_e32 v237, v237
	s_nop 0
	v_mul_f32_e32 v236, v237, v236
	v_mul_f32_e32 v223, v236, v223
	v_add_co_u32_e32 v236, vcc, s54, v86
	v_cvt_pk_bf16_f32 v223, v223, v223
	s_mov_b32 s54, 0x395fe000
	s_nop 0
	v_addc_co_u32_e32 v237, vcc, 0, v87, vcc
	global_store_short v[236:237], v223, off offset:2048
	s_waitcnt vmcnt(28)
	v_lshlrev_b32_e32 v236, 16, v189
	v_mul_f32_e32 v237, 0x3d372713, v236
	v_mul_f32_e32 v237, v237, v236
	v_fma_f32 v237, v237, v236, v236
	v_mul_f32_e32 v237, 0x3f4c422a, v237
	v_add_f32_e32 v237, v237, v237
	v_mul_f32_e32 v237, 0xbfb8aa3b, v237
	v_exp_f32_e32 v237, v237
	v_add_f32_e32 v223, v185, v98
	v_add_f32_e32 v237, 1.0, v237
	v_rcp_f32_e32 v237, v237
	s_nop 0
	v_mul_f32_e32 v236, v237, v236
	v_mul_f32_e32 v223, v236, v223
	v_add_co_u32_e32 v236, vcc, s54, v86
	v_cvt_pk_bf16_f32 v223, v223, v223
	s_mov_b32 s54, 0x395fd000
	s_nop 0
	v_addc_co_u32_e32 v237, vcc, 0, v87, vcc
	global_store_short v[236:237], v223, off offset:2048
	s_waitcnt vmcnt(27)
	v_lshlrev_b32_e32 v237, 16, v191
	v_mul_f32_e32 v238, 0x3d372713, v237
	v_mul_f32_e32 v238, v238, v237
	v_fma_f32 v238, v238, v237, v237
	v_mul_f32_e32 v238, 0x3f4c422a, v238
	v_add_f32_e32 v238, v238, v238
	v_mul_f32_e32 v238, 0xbfb8aa3b, v238
	v_exp_f32_e32 v238, v238
	v_fma_f32 v223, v99, v98, v91
	v_add_f32_e32 v236, v188, v223
	v_fma_f32 v223, v232, v223, v225
	v_add_f32_e32 v238, 1.0, v238
	v_rcp_f32_e32 v238, v238
	s_nop 0
	v_mul_f32_e32 v237, v238, v237
	v_mul_f32_e32 v236, v237, v236
	v_cvt_pk_bf16_f32 v238, v236, v236
	v_add_co_u32_e32 v236, vcc, s54, v86
	s_mov_b32 s54, 0x395fc000
	s_nop 0
	v_addc_co_u32_e32 v237, vcc, 0, v87, vcc
	global_store_short v[236:237], v238, off offset:2048
	s_waitcnt vmcnt(26)
	v_lshlrev_b32_e32 v237, 16, v193
	v_mul_f32_e32 v238, 0x3d372713, v237
	v_mul_f32_e32 v238, v238, v237
	v_fma_f32 v238, v238, v237, v237
	v_mul_f32_e32 v238, 0x3f4c422a, v238
	v_add_f32_e32 v238, v238, v238
	v_mul_f32_e32 v238, 0xbfb8aa3b, v238
	v_exp_f32_e32 v238, v238
	v_add_f32_e32 v236, v190, v223
	v_fma_f32 v223, v227, v223, v101
	v_add_f32_e32 v238, 1.0, v238
	v_rcp_f32_e32 v238, v238
	s_nop 0
	v_mul_f32_e32 v237, v238, v237
	v_mul_f32_e32 v236, v237, v236
	v_cvt_pk_bf16_f32 v238, v236, v236
	v_add_co_u32_e32 v236, vcc, s54, v86
	s_mov_b32 s54, 0x395fb000
	s_nop 0
	v_addc_co_u32_e32 v237, vcc, 0, v87, vcc
	global_store_short v[236:237], v238, off offset:2048
	s_waitcnt vmcnt(25)
; __device__ __forceinline__ unsigned cvt_pk_bf16(float lo, float hi) { unsigned r; asm volatile("v_cvt_pk_bf16_f32 %0, %1, %2" : "=v"(r) : "v"(lo), "v"(hi)); return r; }
; __device__ __forceinline__ float gelu_tanh(float x) { const float z = 0.7978845608028654f * (x + 0.044715f * x * x * x); return x * fast_sigmoid(2.0f * z); }
; __device__ __forceinline__ void lru_item(const Params& p, LAS unsigned char* lds, int item, int tid, int lane, int wave) {
;     ...
;                         bf16* mp_ = MIX + (size_t)rbase * D;
; #pragma unroll
;                         for (int e = 0; e < 16; ++e) { hcur = av[e] * hcur + uv[e];
;                             { const float o_ = (hfv[e] + hcur) * gelu_tanh(__builtin_bit_cast(float, grv[e] << 16)); (mp_ - (size_t)e * D)[moff] = (bf16)pg8::cvt_pk_bf16(o_, o_); } }
	v_lshlrev_b32_e32 v237, 16, v195
	v_mul_f32_e32 v238, 0x3d372713, v237
	v_mul_f32_e32 v238, v238, v237
	v_fma_f32 v238, v238, v237, v237
	v_mul_f32_e32 v238, 0x3f4c422a, v238
	v_add_f32_e32 v238, v238, v238
	v_mul_f32_e32 v238, 0xbfb8aa3b, v238
	v_exp_f32_e32 v238, v238
	v_add_f32_e32 v236, v192, v223
	v_fma_f32 v223, v103, v223, v93
	v_add_f32_e32 v238, 1.0, v238
	v_rcp_f32_e32 v238, v238
	s_nop 0
	v_mul_f32_e32 v237, v238, v237
	v_mul_f32_e32 v236, v237, v236
	v_cvt_pk_bf16_f32 v238, v236, v236
	v_add_co_u32_e32 v236, vcc, s54, v86
	s_mov_b32 s54, 0x395fa000
	s_nop 0
	v_addc_co_u32_e32 v237, vcc, 0, v87, vcc
	global_store_short v[236:237], v238, off offset:2048
	s_waitcnt vmcnt(24)
	v_lshlrev_b32_e32 v237, 16, v197
	v_mul_f32_e32 v238, 0x3d372713, v237
	v_mul_f32_e32 v238, v238, v237
	v_fma_f32 v238, v238, v237, v237
	v_mul_f32_e32 v238, 0x3f4c422a, v238
	v_add_f32_e32 v238, v238, v238
	v_mul_f32_e32 v238, 0xbfb8aa3b, v238
	v_exp_f32_e32 v238, v238
	v_add_f32_e32 v236, v194, v223
	v_fma_f32 v223, v95, v223, v53
	v_add_f32_e32 v238, 1.0, v238
	v_rcp_f32_e32 v238, v238
	s_nop 0
	v_mul_f32_e32 v237, v238, v237
	v_mul_f32_e32 v236, v237, v236
	v_cvt_pk_bf16_f32 v238, v236, v236
	v_add_co_u32_e32 v236, vcc, s54, v86
	s_mov_b32 s54, 0x395f9000
	s_nop 0
	v_addc_co_u32_e32 v237, vcc, 0, v87, vcc
	global_store_short v[236:237], v238, off offset:2048
	s_waitcnt vmcnt(23)
	v_lshlrev_b32_e32 v237, 16, v199
	v_mul_f32_e32 v238, 0x3d372713, v237
	v_mul_f32_e32 v238, v238, v237
	v_fma_f32 v238, v238, v237, v237
	v_mul_f32_e32 v238, 0x3f4c422a, v238
	v_add_f32_e32 v238, v238, v238
	v_mul_f32_e32 v238, 0xbfb8aa3b, v238
	v_exp_f32_e32 v238, v238
	v_add_f32_e32 v236, v196, v223
	v_fma_f32 v223, v233, v223, v226
	v_add_f32_e32 v238, 1.0, v238
	v_rcp_f32_e32 v238, v238
	s_nop 0
	v_mul_f32_e32 v237, v238, v237
	v_mul_f32_e32 v236, v237, v236
	v_cvt_pk_bf16_f32 v238, v236, v236
	v_add_co_u32_e32 v236, vcc, s54, v86
	s_mov_b32 s54, 0x395f8000
	s_nop 0
	v_addc_co_u32_e32 v237, vcc, 0, v87, vcc
	global_store_short v[236:237], v238, off offset:2048
	s_waitcnt vmcnt(22)
	v_lshlrev_b32_e32 v237, 16, v201
	v_mul_f32_e32 v238, 0x3d372713, v237
	v_mul_f32_e32 v238, v238, v237
	v_fma_f32 v238, v238, v237, v237
	v_mul_f32_e32 v238, 0x3f4c422a, v238
	v_add_f32_e32 v238, v238, v238
	v_mul_f32_e32 v238, 0xbfb8aa3b, v238
	v_exp_f32_e32 v238, v238
	v_add_f32_e32 v236, v198, v223
	v_fma_f32 v223, v229, v223, v102
	v_add_f32_e32 v238, 1.0, v238
	v_rcp_f32_e32 v238, v238
	s_nop 0
	v_mul_f32_e32 v237, v238, v237
	v_mul_f32_e32 v236, v237, v236
	v_cvt_pk_bf16_f32 v238, v236, v236
	v_add_co_u32_e32 v236, vcc, s54, v86
	s_mov_b32 s54, 0x395f7000
	s_nop 0
	v_addc_co_u32_e32 v237, vcc, 0, v87, vcc
	global_store_short v[236:237], v238, off offset:2048
	s_waitcnt vmcnt(21)
	v_lshlrev_b32_e32 v237, 16, v203
	v_mul_f32_e32 v238, 0x3d372713, v237
	v_mul_f32_e32 v238, v238, v237
	v_fma_f32 v238, v238, v237, v237
	v_mul_f32_e32 v238, 0x3f4c422a, v238
	v_add_f32_e32 v238, v238, v238
	v_mul_f32_e32 v238, 0xbfb8aa3b, v238
	v_exp_f32_e32 v238, v238
	v_add_f32_e32 v236, v200, v223
	v_fma_f32 v223, v104, v223, v94
	v_add_f32_e32 v238, 1.0, v238
	v_rcp_f32_e32 v238, v238
	s_nop 0
	v_mul_f32_e32 v237, v238, v237
	v_mul_f32_e32 v236, v237, v236
	v_cvt_pk_bf16_f32 v238, v236, v236
	v_add_co_u32_e32 v236, vcc, s54, v86
	s_mov_b32 s54, 0x395f6000
	s_nop 0
	v_addc_co_u32_e32 v237, vcc, 0, v87, vcc
	global_store_short v[236:237], v238, off offset:2048
	s_waitcnt vmcnt(20)
; __device__ __forceinline__ unsigned cvt_pk_bf16(float lo, float hi) { unsigned r; asm volatile("v_cvt_pk_bf16_f32 %0, %1, %2" : "=v"(r) : "v"(lo), "v"(hi)); return r; }
; __device__ __forceinline__ float gelu_tanh(float x) { const float z = 0.7978845608028654f * (x + 0.044715f * x * x * x); return x * fast_sigmoid(2.0f * z); }
; __device__ __forceinline__ void lru_item(const Params& p, LAS unsigned char* lds, int item, int tid, int lane, int wave) {
;     ...
;                         bf16* mp_ = MIX + (size_t)rbase * D;
; #pragma unroll
;                         for (int e = 0; e < 16; ++e) { hcur = av[e] * hcur + uv[e];
;                             { const float o_ = (hfv[e] + hcur) * gelu_tanh(__builtin_bit_cast(float, grv[e] << 16)); (mp_ - (size_t)e * D)[moff] = (bf16)pg8::cvt_pk_bf16(o_, o_); } }
	v_lshlrev_b32_e32 v237, 16, v205
	v_mul_f32_e32 v238, 0x3d372713, v237
	v_mul_f32_e32 v238, v238, v237
	v_fma_f32 v238, v238, v237, v237
	v_mul_f32_e32 v238, 0x3f4c422a, v238
	v_add_f32_e32 v238, v238, v238
	v_mul_f32_e32 v238, 0xbfb8aa3b, v238
	v_exp_f32_e32 v238, v238
	v_add_f32_e32 v236, v202, v223
	v_fma_f32 v223, v96, v223, v90
	v_add_f32_e32 v238, 1.0, v238
	v_rcp_f32_e32 v238, v238
	s_nop 0
	v_mul_f32_e32 v237, v238, v237
	v_mul_f32_e32 v236, v237, v236
	v_cvt_pk_bf16_f32 v238, v236, v236
	v_add_co_u32_e32 v236, vcc, s54, v86
	s_mov_b32 s54, 0x395f5000
	s_nop 0
	v_addc_co_u32_e32 v237, vcc, 0, v87, vcc
	global_store_short v[236:237], v238, off offset:2048
	s_waitcnt vmcnt(19)
	v_lshlrev_b32_e32 v237, 16, v207
	v_mul_f32_e32 v238, 0x3d372713, v237
	v_mul_f32_e32 v238, v238, v237
	v_fma_f32 v238, v238, v237, v237
	v_mul_f32_e32 v238, 0x3f4c422a, v238
	v_add_f32_e32 v238, v238, v238
	v_mul_f32_e32 v238, 0xbfb8aa3b, v238
	v_exp_f32_e32 v238, v238
	v_add_f32_e32 v236, v204, v223
	v_fma_f32 v223, v234, v223, v230
	v_add_f32_e32 v238, 1.0, v238
	v_rcp_f32_e32 v238, v238
	s_nop 0
	v_mul_f32_e32 v237, v238, v237
	v_mul_f32_e32 v236, v237, v236
	v_cvt_pk_bf16_f32 v238, v236, v236
	v_add_co_u32_e32 v236, vcc, s54, v86
	s_mov_b32 s54, 0x395f4000
	s_nop 0
	v_addc_co_u32_e32 v237, vcc, 0, v87, vcc
	global_store_short v[236:237], v238, off offset:2048
	s_waitcnt vmcnt(18)
	v_lshlrev_b32_e32 v237, 16, v209
	v_mul_f32_e32 v238, 0x3d372713, v237
	v_mul_f32_e32 v238, v238, v237
	v_fma_f32 v238, v238, v237, v237
	v_mul_f32_e32 v238, 0x3f4c422a, v238
	v_add_f32_e32 v238, v238, v238
	v_mul_f32_e32 v238, 0xbfb8aa3b, v238
	v_exp_f32_e32 v238, v238
	v_add_f32_e32 v236, v206, v223
	v_fma_f32 v223, v231, v223, v105
	v_add_f32_e32 v238, 1.0, v238
	v_rcp_f32_e32 v238, v238
	s_nop 0
	v_mul_f32_e32 v237, v238, v237
	v_mul_f32_e32 v236, v237, v236
	v_cvt_pk_bf16_f32 v238, v236, v236
	v_add_co_u32_e32 v236, vcc, s54, v86
	s_mov_b32 s54, 0x395f3000
	s_nop 0
	v_addc_co_u32_e32 v237, vcc, 0, v87, vcc
	global_store_short v[236:237], v238, off offset:2048
	s_waitcnt vmcnt(17)
	v_lshlrev_b32_e32 v237, 16, v211
	v_mul_f32_e32 v238, 0x3d372713, v237
	v_mul_f32_e32 v238, v238, v237
	v_fma_f32 v238, v238, v237, v237
	v_mul_f32_e32 v238, 0x3f4c422a, v238
	v_add_f32_e32 v238, v238, v238
	v_mul_f32_e32 v238, 0xbfb8aa3b, v238
	v_exp_f32_e32 v238, v238
	v_add_f32_e32 v236, v208, v223
	v_fma_f32 v223, v107, v223, v97
	v_add_f32_e32 v238, 1.0, v238
	v_rcp_f32_e32 v238, v238
	s_nop 0
	v_mul_f32_e32 v237, v238, v237
	v_mul_f32_e32 v236, v237, v236
	v_cvt_pk_bf16_f32 v238, v236, v236
	v_add_co_u32_e32 v236, vcc, s54, v86
	s_mov_b32 s54, 0x395f2000
	s_nop 0
	v_addc_co_u32_e32 v237, vcc, 0, v87, vcc
	global_store_short v[236:237], v238, off offset:2048
	s_waitcnt vmcnt(16)
	v_lshlrev_b32_e32 v237, 16, v213
	v_mul_f32_e32 v238, 0x3d372713, v237
	v_mul_f32_e32 v238, v238, v237
	v_fma_f32 v238, v238, v237, v237
	v_mul_f32_e32 v238, 0x3f4c422a, v238
	v_add_f32_e32 v238, v238, v238
	v_mul_f32_e32 v238, 0xbfb8aa3b, v238
	v_exp_f32_e32 v238, v238
	v_add_f32_e32 v236, v210, v223
	v_fma_f32 v223, v100, v223, v92
	s_waitcnt vmcnt(15)
	v_add_f32_e32 v223, v212, v223
	v_add_f32_e32 v238, 1.0, v238
	v_rcp_f32_e32 v238, v238
	s_nop 0
	v_mul_f32_e32 v237, v238, v237
	v_mul_f32_e32 v236, v237, v236
	v_cvt_pk_bf16_f32 v238, v236, v236
	v_add_co_u32_e32 v236, vcc, s54, v86
	s_mov_b64 s[54:55], 0
	s_nop 0
	v_addc_co_u32_e32 v237, vcc, 0, v87, vcc
	global_store_short v[236:237], v238, off offset:2048
	s_waitcnt vmcnt(15)
	v_lshlrev_b32_e32 v236, 16, v214
	v_mul_f32_e32 v237, 0x3d372713, v236
	v_mul_f32_e32 v237, v237, v236
	v_fma_f32 v237, v237, v236, v236
	v_mul_f32_e32 v237, 0x3f4c422a, v237
	v_add_f32_e32 v237, v237, v237
	v_mul_f32_e32 v237, 0xbfb8aa3b, v237
	v_exp_f32_e32 v237, v237
	v_add_co_u32_e32 v86, vcc, 0x395f1000, v86
	v_add_f32_e32 v237, 1.0, v237
	v_rcp_f32_e32 v237, v237
	v_addc_co_u32_e32 v87, vcc, 0, v87, vcc
	v_mul_f32_e32 v236, v237, v236
	v_mul_f32_e32 v223, v236, v223
	v_cvt_pk_bf16_f32 v223, v223, v223
	global_store_short v[86:87], v223, off offset:2048

; #define LAS __attribute__((address_space(3)))
; __device__ __forceinline__ void attn_phase(const Params& p, LAS unsigned char* lds, int tid, int lane, int wave) {
;     ...
;             if (h != hcur) {
;                 __syncthreads();
;                 const size_t tb0 = (size_t)((M_LAT + b * CTXL) >> 4);
;                 const int td = wave * 64 + ln;
;                 for (int i = td; i < ATT_HT; i += 512) rpbh[i] = i < 465 ? p.in[IN_RPB][h * 465 + i] * 1.44269504089f : -1e30f;
;                 for (int i = td; i < 2048; i += 512) ckL[i] = KF[(tb0 + (i >> 7)) * 2048 + h * 128 + (i & 127)];
;                 for (int i = td; i < 4096; i += 512) { const int tb = i >> 8, d = (i >> 6) & 3, l_ = i & 63;
;                     ((LAS u32x2*)cvL)[((((tb >> 1) * 4 + d) * 64 + l_) << 1) + (tb & 1)] = VF8[(tb0 + tb) * 4096 + h * 256 + d * 64 + l_]; }
.LBB0_2196:
	s_ashr_i32 s4, s62, 4
	s_cmp_eq_u32 s4, s63
	s_mov_b32 s0, s64
	v_mbcnt_lo_u32_b32 v128, -1, 0
	v_mbcnt_hi_u32_b32 v128, -1, v128
	s_cbranch_scc1 .LBB0_2209
	v_add_u32_e32 v4, s35, v128
	s_lshl_b32 s6, s4, 7
	s_ashr_i32 s7, s6, 31
	s_lshl_b64 s[6:7], s[6:7], 4
	s_add_u32 s6, s26, s6
	s_addc_u32 s7, s27, s7
	v_ashrrev_i32_e32 v6, 7, v4
	v_ashrrev_i32_e32 v7, 31, v6
	v_lshl_add_u64 v[6:7], v[6:7], 0, s[22:23]
	v_and_b32_e32 v5, 0x7f, v4
	v_lshlrev_b64 v[6:7], 15, v[6:7]
	v_lshlrev_b32_e32 v126, 4, v5
	v_lshl_add_u64 v[6:7], s[6:7], 0, v[6:7]
	v_lshl_add_u64 v[6:7], v[6:7], 0, v[126:127]
	s_mov_b64 s[8:9], 0x20000
	global_load_dwordx4 v[180:183], v[6:7], off
	v_lshl_add_u64 v[6:7], s[8:9], 0, v[6:7]
	global_load_dwordx4 v[184:187], v[6:7], off
	v_lshl_add_u64 v[6:7], s[8:9], 0, v[6:7]
	global_load_dwordx4 v[188:191], v[6:7], off
	v_lshl_add_u64 v[6:7], s[8:9], 0, v[6:7]
	global_load_dwordx4 v[192:195], v[6:7], off
	s_lshl_b32 s6, s4, 8
	s_ashr_i32 s7, s6, 31
	s_lshl_b64 s[6:7], s[6:7], 3
	s_add_u32 s6, s28, s6
	s_addc_u32 s7, s29, s7
	v_and_b32_e32 v2, 63, v128
	v_lshlrev_b32_e32 v2, 3, v2
	v_mov_b32_e32 v3, v127
	v_ashrrev_i32_e32 v6, 8, v4
	v_ashrrev_i32_e32 v7, 31, v6
	v_lshl_add_u64 v[8:9], v[6:7], 0, s[22:23]
	v_bfe_u32 v10, v4, 6, 2
	v_lshlrev_b64 v[8:9], 15, v[8:9]
	v_lshlrev_b32_e32 v126, 9, v10
	v_lshl_add_u64 v[8:9], s[6:7], 0, v[8:9]
	v_lshl_add_u64 v[8:9], v[8:9], 0, v[126:127]
	v_lshl_add_u64 v[8:9], v[8:9], 0, v[2:3]
	s_mov_b64 s[8:9], 0x10000
	global_load_dwordx2 v[196:197], v[8:9], off
	v_lshl_add_u64 v[8:9], s[8:9], 0, v[8:9]
	global_load_dwordx2 v[198:199], v[8:9], off
	v_lshl_add_u64 v[8:9], s[8:9], 0, v[8:9]
	global_load_dwordx2 v[200:201], v[8:9], off
	v_lshl_add_u64 v[8:9], s[8:9], 0, v[8:9]
	global_load_dwordx2 v[202:203], v[8:9], off
	v_lshl_add_u64 v[8:9], s[8:9], 0, v[8:9]
	global_load_dwordx2 v[204:205], v[8:9], off
	v_lshl_add_u64 v[8:9], s[8:9], 0, v[8:9]
	global_load_dwordx2 v[206:207], v[8:9], off
	v_lshl_add_u64 v[8:9], s[8:9], 0, v[8:9]
	global_load_dwordx2 v[208:209], v[8:9], off
	v_lshl_add_u64 v[8:9], s[8:9], 0, v[8:9]
	global_load_dwordx2 v[210:211], v[8:9], off
	v_cmp_gt_i32_e32 vcc, s46, v4
	s_waitcnt lgkmcnt(0)
	s_barrier
	s_and_saveexec_b64 s[0:1], vcc
	s_cbranch_execz .LBB0_2202
	s_mul_i32 s10, s4, 0x1d1
	v_lshl_add_u32 v2, v128, 2, s43
	s_mov_b64 s[6:7], 0
	v_mov_b32_e32 v3, v4
	s_branch .LBB0_2200

; #define LAS __attribute__((address_space(3)))
; __device__ __forceinline__ void attn_phase(const Params& p, LAS unsigned char* lds, int tid, int lane, int wave) {
;     ...
;                 for (int i = td; i < ATT_HT; i += 512) rpbh[i] = i < 465 ? p.in[IN_RPB][h * 465 + i] * 1.44269504089f : -1e30f;
;                 for (int i = td; i < 2048; i += 512) ckL[i] = KF[(tb0 + (i >> 7)) * 2048 + h * 128 + (i & 127)];
;                 for (int i = td; i < 4096; i += 512) { const int tb = i >> 8, d = (i >> 6) & 3, l_ = i & 63;
;                     ((LAS u32x2*)cvL)[((((tb >> 1) * 4 + d) * 64 + l_) << 1) + (tb & 1)] = VF8[(tb0 + tb) * 4096 + h * 256 + d * 64 + l_]; }
;                 hcur = h; have_hi = -1;
.LBB0_2202:
	s_or_b64 exec, exec, s[0:1]
	v_lshl_add_u32 v2, v128, 4, s45
	s_waitcnt vmcnt(8)
	ds_write_b128 v2, v[180:183]
	ds_write_b128 v2, v[184:187] offset:8192
	ds_write_b128 v2, v[188:191] offset:16384
	ds_write_b128 v2, v[192:195] offset:24576
	v_and_b32_e32 v2, 63, v128
	v_lshlrev_b32_e32 v5, 4, v2
	v_ashrrev_i32_e32 v6, 8, v4
	v_lshlrev_b32_e32 v6, 3, v6
	v_and_b32_e32 v6, 8, v6
	v_bfe_u32 v10, v4, 6, 2
	v_lshlrev_b32_e32 v10, 10, v10
	v_add3_u32 v6, v10, v5, v6
	v_add_u32_e32 v6, 0x9000, v6
	s_waitcnt vmcnt(0)
	ds_write_b64 v6, v[196:197]
	ds_write_b64 v6, v[198:199] offset:4096
	ds_write_b64 v6, v[200:201] offset:8192
	ds_write_b64 v6, v[202:203] offset:12288
	ds_write_b64 v6, v[204:205] offset:16384
	ds_write_b64 v6, v[206:207] offset:20480
	ds_write_b64 v6, v[208:209] offset:24576
	ds_write_b64 v6, v[210:211] offset:28672
	s_mov_b32 s0, -1
	s_mov_b32 s63, s4
	s_nop 0
	s_nop 0
	s_nop 0
